# combo23: combo22 + forgetting-attention tiles: all 8 K-fragment LDS reads at the tile top and the 16 V-fragment reads issued before the exps (into free VGPRs), so the QK and PV MFMAs no longer wait on
# speedup vs baseline: 1.0062x; 1.0027x over previous
; #define LAS __attribute__((address_space(3)))
; __device__ __forceinline__ float fast_exp2(float x) { return __builtin_amdgcn_exp2f(x); }
; __device__ __forceinline__ int crow(int r, int hi) { return (r & 3) + 8 * (r >> 2) + 4 * hi; }
; template <int TYPE> __device__ __forceinline__ void attn_unit(const AttnCtx& C, int b, int h, int qb, LAS unsigned char* lds, int tid_in, unsigned* counter) {
;     ...
;             if (active) {
;                 f32x16 p0, p1;
;                 const LAS unsigned char* kp = Kb + bo + hi * 1024 + r32 * 16;
; #pragma unroll
;                 for (int d0 = 0; d0 < 4; ++d0) {
;                     const bf16x8 a0 = *(const LAS bf16x8*)(kp + d0 * 2048), a1 = *(const LAS bf16x8*)(kp + d0 * 2048 + 512);
;                     if (d0 == 0) { p0 = MFMA32(a0, qr[0], (TYPE == 1 ? cvec : zvec)); p1 = MFMA32(a1, qr[0], (TYPE == 1 ? cvec : zvec)); }
;                     else { p0 = MFMA32(a0, qr[d0], p0); p1 = MFMA32(a1, qr[d0], p1); }
;                 }
;                 const int xi = sq - 64 * t - 4 * hi;
;                 if (TYPE == 0) {
;                     const float xf = (float)xi;
; #pragma unroll
;                     for (int r = 0; r < 16; ++r) { const float c = (float)((r & 3) + 8 * (r >> 2));
;                         p0[r] = fast_exp2(p0[r] - sl2 * fabsf(xf - c)); p1[r] = fast_exp2(p1[r] - sl2 * fabsf(xf - (c + 32.f))); }
;                 } else if (TYPE == 1) {
;                     const LAS float* fp = Fb + (t & 3) * 64 + 4 * hi;
; #pragma unroll
;                     for (int g = 0; g < 4; ++g) { const f32x4 fa = *(const LAS f32x4*)(fp + 8 * g), fb2 = *(const LAS f32x4*)(fp + 32 + 8 * g);
; #pragma unroll
;                         for (int i = 0; i < 4; i += 2) {
;                             const f32x2_t d0_ = (f32x2_t){p0[4 * g + i], p0[4 * g + i + 1]} - (f32x2_t){fa[i], fa[i + 1]}, d1_ = (f32x2_t){p1[4 * g + i], p1[4 * g + i + 1]} - (f32x2_t){fb2[i], fb2[i + 1]};
;                             p0[4 * g + i] = fast_exp2(d0_[0]); p0[4 * g + i + 1] = fast_exp2(d0_[1]); p1[4 * g + i] = fast_exp2(d1_[0]); p1[4 * g + i + 1] = fast_exp2(d1_[1]); } }
;                     if (t == cq) { const int qrel = 32 * (w & 1) + r32;
; #pragma unroll
;                         for (int r = 0; r < 16; ++r) { const int kv = crow(r, hi); if (kv > qrel) p0[r] = 0.f; if (kv + 32 > qrel) p1[r] = 0.f; } }
.LBB0_420:
	s_cmp_le_i32 s9, s2
	s_cselect_b64 s[0:1], -1, 0
	s_cmp_ge_u32 s9, s89
	s_cselect_b64 s[94:95], -1, 0
	s_or_b64 s[94:95], s[82:83], s[94:95]
	s_and_b64 s[0:1], s[0:1], s[94:95]
	s_andn2_b64 vcc, exec, s[0:1]
	s_cbranch_vccnz .LBB0_424
	v_add_u32_e32 v134, s79, v129
	v_add_u32_e32 v246, s79, v126
	ds_read_b128 v[214:217], v134
	ds_read_b128 v[218:221], v134 offset:512
	ds_read_b128 v[222:225], v134 offset:2048
	ds_read_b128 v[226:229], v134 offset:2560
	ds_read_b128 v[230:233], v134 offset:4096
	ds_read_b128 v[234:237], v134 offset:4608
	ds_read_b128 v[238:241], v134 offset:6144
	ds_read_b128 v[242:245], v134 offset:6656
	v_lshl_add_u32 v142, s8, 8, v128
	s_add_i32 s0, s6, s92
	s_cmp_lg_u32 s0, 2
	s_waitcnt vmcnt(7) lgkmcnt(6)
	v_mfma_f32_32x32x16_bf16 v[64:79], v[214:217], v[80:83], v[32:47]
	v_mfma_f32_32x32x16_bf16 v[48:63], v[218:221], v[80:83], v[32:47]
	s_waitcnt vmcnt(6) lgkmcnt(4)
	v_mfma_f32_32x32x16_bf16 v[64:79], v[222:225], v[84:87], v[64:79]
	v_mfma_f32_32x32x16_bf16 v[48:63], v[226:229], v[84:87], v[48:63]
	s_waitcnt vmcnt(5) lgkmcnt(2)
	v_mfma_f32_32x32x16_bf16 v[64:79], v[230:233], v[88:91], v[64:79]
	v_mfma_f32_32x32x16_bf16 v[48:63], v[234:237], v[88:91], v[48:63]
	s_waitcnt vmcnt(4) lgkmcnt(0)
	v_mfma_f32_32x32x16_bf16 v[64:79], v[238:241], v[92:95], v[64:79]
	ds_read_b128 v[130:133], v142
	ds_read_b128 v[138:141], v142 offset:32
	ds_read_b128 v[146:149], v142 offset:128
	ds_read_b128 v[166:169], v142 offset:160
	s_waitcnt lgkmcnt(4)
	v_mfma_f32_32x32x16_bf16 v[48:63], v[242:245], v[92:95], v[48:63]
	s_waitcnt lgkmcnt(2)
	s_nop 4
	v_add_f32_e64 v68, v68, -v138
	v_add_f32_e64 v69, v69, -v139
	v_add_f32_e64 v70, v70, -v140
	v_add_f32_e64 v71, v71, -v141
	v_pk_add_f32 v[64:65], v[64:65], v[130:131] neg_lo:[0,1] neg_hi:[0,1]
	v_pk_add_f32 v[66:67], v[66:67], v[132:133] neg_lo:[0,1] neg_hi:[0,1]
	ds_read_b128 v[130:133], v142 offset:64
	ds_read_b128 v[134:137], v142 offset:192
	v_exp_f32_e32 v64, v64
	s_waitcnt lgkmcnt(2)
	v_pk_add_f32 v[138:139], v[54:55], v[168:169] neg_lo:[0,1] neg_hi:[0,1]
	v_pk_add_f32 v[48:49], v[48:49], v[146:147] neg_lo:[0,1] neg_hi:[0,1]
	v_pk_add_f32 v[50:51], v[50:51], v[148:149] neg_lo:[0,1] neg_hi:[0,1]
	v_exp_f32_e32 v54, v70
	v_exp_f32_e32 v55, v71
	v_exp_f32_e32 v70, v138
	v_exp_f32_e32 v71, v139
	ds_read_b128 v[138:141], v142 offset:96
	ds_read_b128 v[146:149], v142 offset:224
	v_pk_add_f32 v[52:53], v[52:53], v[166:167] neg_lo:[0,1] neg_hi:[0,1]
	s_waitcnt lgkmcnt(3)
	v_pk_add_f32 v[72:73], v[72:73], v[130:131] neg_lo:[0,1] neg_hi:[0,1]
	s_waitcnt lgkmcnt(2)
	v_pk_add_f32 v[56:57], v[56:57], v[134:135] neg_lo:[0,1] neg_hi:[0,1]
	v_pk_add_f32 v[74:75], v[74:75], v[132:133] neg_lo:[0,1] neg_hi:[0,1]
	v_pk_add_f32 v[58:59], v[58:59], v[136:137] neg_lo:[0,1] neg_hi:[0,1]
	s_waitcnt lgkmcnt(1)
	v_pk_add_f32 v[76:77], v[76:77], v[138:139] neg_lo:[0,1] neg_hi:[0,1]
	s_waitcnt lgkmcnt(0)
	ds_read_b64_tr_b16 v[214:215], v246 offset:32768
	ds_read_b64_tr_b16 v[216:217], v246 offset:33280
	ds_read_b64_tr_b16 v[218:219], v246 offset:33792
	ds_read_b64_tr_b16 v[220:221], v246 offset:34304
	ds_read_b64_tr_b16 v[222:223], v246 offset:34816
	ds_read_b64_tr_b16 v[224:225], v246 offset:35328
	ds_read_b64_tr_b16 v[226:227], v246 offset:35840
	ds_read_b64_tr_b16 v[228:229], v246 offset:36352
	ds_read_b64_tr_b16 v[230:231], v246 offset:36864
	ds_read_b64_tr_b16 v[232:233], v246 offset:37376
	ds_read_b64_tr_b16 v[234:235], v246 offset:37888
	ds_read_b64_tr_b16 v[236:237], v246 offset:38400
	ds_read_b64_tr_b16 v[238:239], v246 offset:38912
	ds_read_b64_tr_b16 v[240:241], v246 offset:39424
	ds_read_b64_tr_b16 v[242:243], v246 offset:39936
	ds_read_b64_tr_b16 v[244:245], v246 offset:40448
	v_pk_add_f32 v[60:61], v[60:61], v[146:147] neg_lo:[0,1] neg_hi:[0,1]
	v_pk_add_f32 v[78:79], v[78:79], v[140:141] neg_lo:[0,1] neg_hi:[0,1]
	v_pk_add_f32 v[62:63], v[62:63], v[148:149] neg_lo:[0,1] neg_hi:[0,1]
	v_exp_f32_e32 v65, v65
	v_exp_f32_e32 v48, v48
	v_exp_f32_e32 v49, v49
	v_exp_f32_e32 v66, v66
	v_exp_f32_e32 v67, v67
	v_exp_f32_e32 v50, v50
	v_exp_f32_e32 v51, v51
	v_exp_f32_e32 v68, v68
	v_exp_f32_e32 v69, v69
	v_exp_f32_e32 v52, v52
	v_exp_f32_e32 v53, v53
	v_exp_f32_e32 v72, v72
	v_exp_f32_e32 v73, v73
	v_exp_f32_e32 v56, v56
	v_exp_f32_e32 v57, v57
	v_exp_f32_e32 v74, v74
	v_exp_f32_e32 v75, v75
	v_exp_f32_e32 v58, v58
	v_exp_f32_e32 v59, v59
	v_exp_f32_e32 v76, v76
	v_exp_f32_e32 v77, v77
	v_exp_f32_e32 v60, v60
	v_exp_f32_e32 v61, v61
	v_exp_f32_e32 v78, v78
	v_exp_f32_e32 v79, v79
	v_exp_f32_e32 v62, v62
	v_exp_f32_e32 v63, v63
	s_cbranch_scc1 .LBB0_423
	v_readlane_b32 s0, v251, 35
	v_readlane_b32 s1, v251, 36
	v_cndmask_b32_e64 v48, v48, 0, s[10:11]
	v_cndmask_b32_e64 v65, 0, v65, s[12:13]
	v_cndmask_b32_e64 v130, v64, 0, s[0:1]
	v_cndmask_b32_e64 v64, v130, v64, s[12:13]
	v_cndmask_b32_e64 v49, v49, 0, s[14:15]
	v_cndmask_b32_e64 v66, v66, 0, s[16:17]
	v_cndmask_b32_e64 v50, v50, 0, s[18:19]
	v_cndmask_b32_e64 v67, v67, 0, s[20:21]
	v_cndmask_b32_e64 v51, v51, 0, s[22:23]
	v_cndmask_b32_e64 v68, v68, 0, s[24:25]
	v_cndmask_b32_e64 v52, v52, 0, s[26:27]
	v_cndmask_b32_e64 v69, v69, 0, s[28:29]
	v_cndmask_b32_e64 v53, v53, 0, s[30:31]
	v_cndmask_b32_e64 v54, v54, 0, s[34:35]
	v_cndmask_b32_e64 v70, v70, 0, s[36:37]
	v_cndmask_b32_e64 v55, v55, 0, s[38:39]
	v_cndmask_b32_e64 v71, v71, 0, s[40:41]
	v_cndmask_b32_e64 v72, v72, 0, s[42:43]
	v_cndmask_b32_e64 v56, v56, 0, s[44:45]
	v_cndmask_b32_e64 v73, v73, 0, s[46:47]
	v_cndmask_b32_e64 v57, v57, 0, s[48:49]
	v_cndmask_b32_e64 v74, v74, 0, s[50:51]
	v_cndmask_b32_e64 v58, v58, 0, s[52:53]
	v_cndmask_b32_e64 v75, v75, 0, s[54:55]
	v_cndmask_b32_e64 v59, v59, 0, s[56:57]
	v_cndmask_b32_e64 v76, v76, 0, s[58:59]
	v_cndmask_b32_e64 v60, v60, 0, s[60:61]
	v_cndmask_b32_e64 v77, v77, 0, s[62:63]
	v_cndmask_b32_e64 v61, v61, 0, s[64:65]
	v_cndmask_b32_e64 v78, v78, 0, s[66:67]
	v_cndmask_b32_e64 v62, v62, 0, s[68:69]
	v_cndmask_b32_e64 v79, v79, 0, s[70:71]
	v_cndmask_b32_e64 v63, v63, 0, s[72:73]
; #define LAS __attribute__((address_space(3)))
; __device__ __forceinline__ unsigned pk2(float lo, float hi) { f32x2_t v = {lo, hi}; bf16x2_t b = __builtin_convertvector(v, bf16x2_t); return __builtin_bit_cast(unsigned, b); }
; #define MFMA32(a, b, c) __builtin_amdgcn_mfma_f32_32x32x16_bf16((a), (b), (c), 0, 0, 0)
; __device__ __forceinline__ s16x4 vtr(const LAS unsigned char* p) { return __builtin_bit_cast(s16x4, __builtin_amdgcn_ds_read_tr16_b64_v4i16((LAS v4i16_t*)p)); }
; template <int TYPE> __device__ __forceinline__ void attn_unit(const AttnCtx& C, int b, int h, int qb, LAS unsigned char* lds, int tid_in, unsigned* counter) {
;     ...
;                 f32x2_t a2 = {0.f, 0.f};
; #pragma unroll
;                 for (int r = 0; r < 16; r += 2) { a2 += (f32x2_t){p0[r], p0[r + 1]}; a2 += (f32x2_t){p1[r], p1[r + 1]}; }
;                 lsum += a2[0] + a2[1];
;                 bf16x8 pa[4];
; #pragma unroll
;                 for (int s = 0; s < 2; ++s) {
;                     u32x4 a, c2;
;                     a.x = pk2(p0[8 * s + 0], p0[8 * s + 1]); a.y = pk2(p0[8 * s + 2], p0[8 * s + 3]); a.z = pk2(p0[8 * s + 4], p0[8 * s + 5]); a.w = pk2(p0[8 * s + 6], p0[8 * s + 7]);
;                     c2.x = pk2(p1[8 * s + 0], p1[8 * s + 1]); c2.y = pk2(p1[8 * s + 2], p1[8 * s + 3]); c2.z = pk2(p1[8 * s + 4], p1[8 * s + 5]); c2.w = pk2(p1[8 * s + 6], p1[8 * s + 7]);
;                     pa[s] = __builtin_bit_cast(bf16x8, a); pa[2 + s] = __builtin_bit_cast(bf16x8, c2);
;                 }
;                 const LAS unsigned char* vp = Vb + bo + vb0;
; #pragma unroll
;                 for (int dh = 0; dh < 2; ++dh)
; #pragma unroll
;                     for (int ks = 0; ks < 4; ++ks) {
;                         const s16x4 lo = vtr(vp + dh * 4096 + ks * 1024), hh = vtr(vp + dh * 4096 + ks * 1024 + 512);
;                         const bf16x8 vf = {lo[0], lo[1], lo[2], lo[3], hh[0], hh[1], hh[2], hh[3]};
;                         o[dh] = MFMA32(pa[ks], vf, o[dh]);
;                     }
.LBB0_423:
	v_pk_add_f32 v[130:131], v[64:65], 0 op_sel_hi:[1,0]
	v_cvt_pk_bf16_f32 v64, v64, v65
	v_pk_add_f32 v[130:131], v[48:49], v[130:131]
	v_cvt_pk_bf16_f32 v65, v66, v67
	v_pk_add_f32 v[130:131], v[66:67], v[130:131]
	v_cvt_pk_bf16_f32 v66, v68, v69
	v_pk_add_f32 v[130:131], v[50:51], v[130:131]
	v_cvt_pk_bf16_f32 v67, v54, v55
	v_pk_add_f32 v[130:131], v[68:69], v[130:131]
	v_add_u32_e32 v68, s79, v126
	v_pk_add_f32 v[130:131], v[52:53], v[130:131]
	v_cvt_pk_bf16_f32 v48, v48, v49
	v_pk_add_f32 v[130:131], v[54:55], v[130:131]
	v_cvt_pk_bf16_f32 v49, v50, v51
	v_pk_add_f32 v[130:131], v[70:71], v[130:131]
	v_cvt_pk_bf16_f32 v50, v52, v53
	v_pk_add_f32 v[130:131], v[72:73], v[130:131]
	v_cvt_pk_bf16_f32 v52, v72, v73
	v_pk_add_f32 v[130:131], v[56:57], v[130:131]
	v_cvt_pk_bf16_f32 v56, v56, v57
	v_pk_add_f32 v[130:131], v[74:75], v[130:131]
	v_cvt_pk_bf16_f32 v57, v58, v59
	v_pk_add_f32 v[130:131], v[58:59], v[130:131]
	v_cvt_pk_bf16_f32 v58, v60, v61
	v_pk_add_f32 v[130:131], v[76:77], v[130:131]
	v_cvt_pk_bf16_f32 v59, v62, v63
	v_pk_add_f32 v[130:131], v[60:61], v[130:131]
	v_cvt_pk_bf16_f32 v53, v74, v75
	v_pk_add_f32 v[130:131], v[78:79], v[130:131]
	v_cvt_pk_bf16_f32 v54, v76, v77
	v_pk_add_f32 v[130:131], v[62:63], v[130:131]
	s_waitcnt lgkmcnt(0)
	v_mfma_f32_32x32x16_bf16 v[16:31], v[64:67], v[214:217], v[16:31]
	v_cvt_pk_bf16_f32 v55, v78, v79
	v_cvt_pk_bf16_f32 v51, v70, v71
	v_add_f32_e32 v130, v130, v131
	v_add_f32_e32 v127, v127, v130
	s_waitcnt lgkmcnt(0)
	v_mfma_f32_32x32x16_bf16 v[16:31], v[52:55], v[218:221], v[16:31]
	s_waitcnt lgkmcnt(0)
	v_mfma_f32_32x32x16_bf16 v[16:31], v[48:51], v[222:225], v[16:31]
	s_waitcnt lgkmcnt(0)
	v_mfma_f32_32x32x16_bf16 v[16:31], v[56:59], v[226:229], v[16:31]
	s_waitcnt lgkmcnt(0)
	v_mfma_f32_32x32x16_bf16 v[0:15], v[64:67], v[230:233], v[0:15]
	s_waitcnt lgkmcnt(0)
	v_mfma_f32_32x32x16_bf16 v[0:15], v[52:55], v[234:237], v[0:15]
	s_waitcnt lgkmcnt(0)
	v_mfma_f32_32x32x16_bf16 v[0:15], v[48:51], v[238:241], v[0:15]
	s_waitcnt lgkmcnt(0)
	v_mfma_f32_32x32x16_bf16 v[0:15], v[56:59], v[242:245], v[0:15]

; #define LAS __attribute__((address_space(3)))
; __device__ __forceinline__ float fast_exp2(float x) { return __builtin_amdgcn_exp2f(x); }
; __device__ __forceinline__ int crow(int r, int hi) { return (r & 3) + 8 * (r >> 2) + 4 * hi; }
; template <int TYPE> __device__ __forceinline__ void attn_unit(const AttnCtx& C, int b, int h, int qb, LAS unsigned char* lds, int tid_in, unsigned* counter) {
;     ...
;             if (active) {
;                 f32x16 p0, p1;
;                 const LAS unsigned char* kp = Kb + bo + hi * 1024 + r32 * 16;
; #pragma unroll
;                 for (int d0 = 0; d0 < 4; ++d0) {
;                     const bf16x8 a0 = *(const LAS bf16x8*)(kp + d0 * 2048), a1 = *(const LAS bf16x8*)(kp + d0 * 2048 + 512);
;                     if (d0 == 0) { p0 = MFMA32(a0, qr[0], (TYPE == 1 ? cvec : zvec)); p1 = MFMA32(a1, qr[0], (TYPE == 1 ? cvec : zvec)); }
;                     else { p0 = MFMA32(a0, qr[d0], p0); p1 = MFMA32(a1, qr[d0], p1); }
;                 }
;                 const int xi = sq - 64 * t - 4 * hi;
;                 if (TYPE == 0) {
;                     const float xf = (float)xi;
; #pragma unroll
;                     for (int r = 0; r < 16; ++r) { const float c = (float)((r & 3) + 8 * (r >> 2));
;                         p0[r] = fast_exp2(p0[r] - sl2 * fabsf(xf - c)); p1[r] = fast_exp2(p1[r] - sl2 * fabsf(xf - (c + 32.f))); }
;                 } else if (TYPE == 1) {
;                     const LAS float* fp = Fb + (t & 3) * 64 + 4 * hi;
; #pragma unroll
;                     for (int g = 0; g < 4; ++g) { const f32x4 fa = *(const LAS f32x4*)(fp + 8 * g), fb2 = *(const LAS f32x4*)(fp + 32 + 8 * g);
; #pragma unroll
;                         for (int i = 0; i < 4; i += 2) {
;                             const f32x2_t d0_ = (f32x2_t){p0[4 * g + i], p0[4 * g + i + 1]} - (f32x2_t){fa[i], fa[i + 1]}, d1_ = (f32x2_t){p1[4 * g + i], p1[4 * g + i + 1]} - (f32x2_t){fb2[i], fb2[i + 1]};
;                             p0[4 * g + i] = fast_exp2(d0_[0]); p0[4 * g + i + 1] = fast_exp2(d0_[1]); p1[4 * g + i] = fast_exp2(d1_[0]); p1[4 * g + i + 1] = fast_exp2(d1_[1]); } }
;                     if (t == cq) { const int qrel = 32 * (w & 1) + r32;
; #pragma unroll
;                         for (int r = 0; r < 16; ++r) { const int kv = crow(r, hi); if (kv > qrel) p0[r] = 0.f; if (kv + 32 > qrel) p1[r] = 0.f; } }
.LBB0_1346:
	s_cmp_le_i32 s11, s86
	s_cselect_b64 s[0:1], -1, 0
	s_cmp_ge_u32 s11, s97
	s_cselect_b64 s[2:3], -1, 0
	s_or_b64 s[2:3], s[82:83], s[2:3]
	s_and_b64 s[0:1], s[0:1], s[2:3]
	s_andn2_b64 vcc, exec, s[0:1]
	s_cbranch_vccnz .LBB0_1350
	v_add_u32_e32 v134, s79, v128
	v_add_u32_e32 v246, s79, v126
	ds_read_b128 v[214:217], v134
	ds_read_b128 v[218:221], v134 offset:512
	ds_read_b128 v[222:225], v134 offset:2048
	ds_read_b128 v[226:229], v134 offset:2560
	ds_read_b128 v[230:233], v134 offset:4096
	ds_read_b128 v[234:237], v134 offset:4608
	ds_read_b128 v[238:241], v134 offset:6144
	ds_read_b128 v[242:245], v134 offset:6656
	v_lshl_add_u32 v142, s10, 8, v127
	s_add_i32 s0, s96, s87
	s_cmp_lg_u32 s0, 2
	s_waitcnt vmcnt(7) lgkmcnt(6)
	v_mfma_f32_32x32x16_bf16 v[64:79], v[214:217], v[80:83], v[32:47]
	v_mfma_f32_32x32x16_bf16 v[48:63], v[218:221], v[80:83], v[32:47]
	s_waitcnt vmcnt(6) lgkmcnt(4)
	v_mfma_f32_32x32x16_bf16 v[64:79], v[222:225], v[84:87], v[64:79]
	v_mfma_f32_32x32x16_bf16 v[48:63], v[226:229], v[84:87], v[48:63]
	s_waitcnt vmcnt(5) lgkmcnt(2)
	v_mfma_f32_32x32x16_bf16 v[64:79], v[230:233], v[88:91], v[64:79]
	v_mfma_f32_32x32x16_bf16 v[48:63], v[234:237], v[88:91], v[48:63]
	s_waitcnt vmcnt(4) lgkmcnt(0)
	v_mfma_f32_32x32x16_bf16 v[64:79], v[238:241], v[92:95], v[64:79]
	ds_read_b128 v[130:133], v142
	ds_read_b128 v[138:141], v142 offset:32
	ds_read_b128 v[146:149], v142 offset:128
	ds_read_b128 v[166:169], v142 offset:160
	s_waitcnt lgkmcnt(4)
	v_mfma_f32_32x32x16_bf16 v[48:63], v[242:245], v[92:95], v[48:63]
	s_waitcnt lgkmcnt(2)
	s_nop 4
	v_add_f32_e64 v68, v68, -v138
	v_add_f32_e64 v69, v69, -v139
	v_add_f32_e64 v70, v70, -v140
	v_add_f32_e64 v71, v71, -v141
	v_pk_add_f32 v[64:65], v[64:65], v[130:131] neg_lo:[0,1] neg_hi:[0,1]
	v_pk_add_f32 v[66:67], v[66:67], v[132:133] neg_lo:[0,1] neg_hi:[0,1]
	ds_read_b128 v[130:133], v142 offset:64
	ds_read_b128 v[134:137], v142 offset:192
	v_exp_f32_e32 v64, v64
	s_waitcnt lgkmcnt(2)
	v_pk_add_f32 v[138:139], v[54:55], v[168:169] neg_lo:[0,1] neg_hi:[0,1]
	v_pk_add_f32 v[48:49], v[48:49], v[146:147] neg_lo:[0,1] neg_hi:[0,1]
	v_pk_add_f32 v[50:51], v[50:51], v[148:149] neg_lo:[0,1] neg_hi:[0,1]
	v_exp_f32_e32 v54, v70
	v_exp_f32_e32 v55, v71
	v_exp_f32_e32 v70, v138
	v_exp_f32_e32 v71, v139
	ds_read_b128 v[138:141], v142 offset:96
	ds_read_b128 v[146:149], v142 offset:224
	v_pk_add_f32 v[52:53], v[52:53], v[166:167] neg_lo:[0,1] neg_hi:[0,1]
	s_waitcnt lgkmcnt(3)
	v_pk_add_f32 v[72:73], v[72:73], v[130:131] neg_lo:[0,1] neg_hi:[0,1]
	s_waitcnt lgkmcnt(2)
	v_pk_add_f32 v[56:57], v[56:57], v[134:135] neg_lo:[0,1] neg_hi:[0,1]
	v_pk_add_f32 v[74:75], v[74:75], v[132:133] neg_lo:[0,1] neg_hi:[0,1]
	v_pk_add_f32 v[58:59], v[58:59], v[136:137] neg_lo:[0,1] neg_hi:[0,1]
	s_waitcnt lgkmcnt(1)
	v_pk_add_f32 v[76:77], v[76:77], v[138:139] neg_lo:[0,1] neg_hi:[0,1]
	s_waitcnt lgkmcnt(0)
	ds_read_b64_tr_b16 v[214:215], v246 offset:32768
	ds_read_b64_tr_b16 v[216:217], v246 offset:33280
	ds_read_b64_tr_b16 v[218:219], v246 offset:33792
	ds_read_b64_tr_b16 v[220:221], v246 offset:34304
	ds_read_b64_tr_b16 v[222:223], v246 offset:34816
	ds_read_b64_tr_b16 v[224:225], v246 offset:35328
	ds_read_b64_tr_b16 v[226:227], v246 offset:35840
	ds_read_b64_tr_b16 v[228:229], v246 offset:36352
	ds_read_b64_tr_b16 v[230:231], v246 offset:36864
	ds_read_b64_tr_b16 v[232:233], v246 offset:37376
	ds_read_b64_tr_b16 v[234:235], v246 offset:37888
	ds_read_b64_tr_b16 v[236:237], v246 offset:38400
	ds_read_b64_tr_b16 v[238:239], v246 offset:38912
	ds_read_b64_tr_b16 v[240:241], v246 offset:39424
	ds_read_b64_tr_b16 v[242:243], v246 offset:39936
	ds_read_b64_tr_b16 v[244:245], v246 offset:40448
	v_pk_add_f32 v[60:61], v[60:61], v[146:147] neg_lo:[0,1] neg_hi:[0,1]
	v_pk_add_f32 v[78:79], v[78:79], v[140:141] neg_lo:[0,1] neg_hi:[0,1]
	v_pk_add_f32 v[62:63], v[62:63], v[148:149] neg_lo:[0,1] neg_hi:[0,1]
	v_exp_f32_e32 v65, v65
	v_exp_f32_e32 v48, v48
	v_exp_f32_e32 v49, v49
	v_exp_f32_e32 v66, v66
	v_exp_f32_e32 v67, v67
	v_exp_f32_e32 v50, v50
	v_exp_f32_e32 v51, v51
	v_exp_f32_e32 v68, v68
	v_exp_f32_e32 v69, v69
	v_exp_f32_e32 v52, v52
	v_exp_f32_e32 v53, v53
	v_exp_f32_e32 v72, v72
	v_exp_f32_e32 v73, v73
	v_exp_f32_e32 v56, v56
	v_exp_f32_e32 v57, v57
	v_exp_f32_e32 v74, v74
	v_exp_f32_e32 v75, v75
	v_exp_f32_e32 v58, v58
	v_exp_f32_e32 v59, v59
	v_exp_f32_e32 v76, v76
	v_exp_f32_e32 v77, v77
	v_exp_f32_e32 v60, v60
	v_exp_f32_e32 v61, v61
	v_exp_f32_e32 v78, v78
	v_exp_f32_e32 v79, v79
	v_exp_f32_e32 v62, v62
	v_exp_f32_e32 v63, v63
	s_cbranch_scc1 .LBB0_1349
	v_readlane_b32 s0, v251, 35
	v_readlane_b32 s1, v251, 36
	v_cndmask_b32_e64 v48, v48, 0, s[12:13]
	v_cndmask_b32_e64 v65, 0, v65, s[14:15]
	v_cndmask_b32_e64 v130, v64, 0, s[0:1]
	v_cndmask_b32_e64 v64, v130, v64, s[14:15]
	v_cndmask_b32_e64 v49, v49, 0, s[16:17]
	v_cndmask_b32_e64 v66, v66, 0, s[18:19]
	v_cndmask_b32_e64 v50, v50, 0, s[20:21]
	v_cndmask_b32_e64 v67, v67, 0, s[22:23]
	v_cndmask_b32_e64 v51, v51, 0, s[24:25]
	v_cndmask_b32_e64 v68, v68, 0, s[26:27]
	v_cndmask_b32_e64 v52, v52, 0, s[28:29]
	v_cndmask_b32_e64 v69, v69, 0, s[30:31]
	v_cndmask_b32_e64 v53, v53, 0, s[34:35]
	v_cndmask_b32_e64 v54, v54, 0, s[36:37]
	v_cndmask_b32_e64 v70, v70, 0, s[38:39]
	v_cndmask_b32_e64 v55, v55, 0, s[40:41]
	v_cndmask_b32_e64 v71, v71, 0, s[42:43]
	v_cndmask_b32_e64 v72, v72, 0, s[44:45]
	v_cndmask_b32_e64 v56, v56, 0, s[46:47]
	v_cndmask_b32_e64 v73, v73, 0, s[48:49]
	v_cndmask_b32_e64 v57, v57, 0, s[50:51]
	v_cndmask_b32_e64 v74, v74, 0, s[52:53]
	v_cndmask_b32_e64 v58, v58, 0, s[54:55]
	v_cndmask_b32_e64 v75, v75, 0, s[56:57]
	v_cndmask_b32_e64 v59, v59, 0, s[58:59]
	v_cndmask_b32_e64 v76, v76, 0, s[60:61]
	v_cndmask_b32_e64 v60, v60, 0, s[62:63]
	v_cndmask_b32_e64 v77, v77, 0, s[64:65]
	v_cndmask_b32_e64 v61, v61, 0, s[66:67]
	v_cndmask_b32_e64 v78, v78, 0, s[68:69]
	v_cndmask_b32_e64 v62, v62, 0, s[70:71]
	v_cndmask_b32_e64 v79, v79, 0, s[72:73]
	v_cndmask_b32_e64 v63, v63, 0, s[74:75]
; #define LAS __attribute__((address_space(3)))
; __device__ __forceinline__ unsigned pk2(float lo, float hi) { f32x2_t v = {lo, hi}; bf16x2_t b = __builtin_convertvector(v, bf16x2_t); return __builtin_bit_cast(unsigned, b); }
; #define MFMA32(a, b, c) __builtin_amdgcn_mfma_f32_32x32x16_bf16((a), (b), (c), 0, 0, 0)
; __device__ __forceinline__ s16x4 vtr(const LAS unsigned char* p) { return __builtin_bit_cast(s16x4, __builtin_amdgcn_ds_read_tr16_b64_v4i16((LAS v4i16_t*)p)); }
; template <int TYPE> __device__ __forceinline__ void attn_unit(const AttnCtx& C, int b, int h, int qb, LAS unsigned char* lds, int tid_in, unsigned* counter) {
;     ...
;                 f32x2_t a2 = {0.f, 0.f};
; #pragma unroll
;                 for (int r = 0; r < 16; r += 2) { a2 += (f32x2_t){p0[r], p0[r + 1]}; a2 += (f32x2_t){p1[r], p1[r + 1]}; }
;                 lsum += a2[0] + a2[1];
;                 bf16x8 pa[4];
; #pragma unroll
;                 for (int s = 0; s < 2; ++s) {
;                     u32x4 a, c2;
;                     a.x = pk2(p0[8 * s + 0], p0[8 * s + 1]); a.y = pk2(p0[8 * s + 2], p0[8 * s + 3]); a.z = pk2(p0[8 * s + 4], p0[8 * s + 5]); a.w = pk2(p0[8 * s + 6], p0[8 * s + 7]);
;                     c2.x = pk2(p1[8 * s + 0], p1[8 * s + 1]); c2.y = pk2(p1[8 * s + 2], p1[8 * s + 3]); c2.z = pk2(p1[8 * s + 4], p1[8 * s + 5]); c2.w = pk2(p1[8 * s + 6], p1[8 * s + 7]);
;                     pa[s] = __builtin_bit_cast(bf16x8, a); pa[2 + s] = __builtin_bit_cast(bf16x8, c2);
;                 }
;                 const LAS unsigned char* vp = Vb + bo + vb0;
; #pragma unroll
;                 for (int dh = 0; dh < 2; ++dh)
; #pragma unroll
;                     for (int ks = 0; ks < 4; ++ks) {
;                         const s16x4 lo = vtr(vp + dh * 4096 + ks * 1024), hh = vtr(vp + dh * 4096 + ks * 1024 + 512);
;                         const bf16x8 vf = {lo[0], lo[1], lo[2], lo[3], hh[0], hh[1], hh[2], hh[3]};
;                         o[dh] = MFMA32(pa[ks], vf, o[dh]);
;                     }
.LBB0_1349:
	v_pk_add_f32 v[130:131], v[64:65], 0 op_sel_hi:[1,0]
	v_cvt_pk_bf16_f32 v64, v64, v65
	v_pk_add_f32 v[130:131], v[48:49], v[130:131]
	v_cvt_pk_bf16_f32 v65, v66, v67
	v_pk_add_f32 v[130:131], v[66:67], v[130:131]
	v_cvt_pk_bf16_f32 v66, v68, v69
	v_pk_add_f32 v[130:131], v[50:51], v[130:131]
	v_cvt_pk_bf16_f32 v67, v54, v55
	v_pk_add_f32 v[130:131], v[68:69], v[130:131]
	v_add_u32_e32 v68, s79, v126
	v_pk_add_f32 v[130:131], v[52:53], v[130:131]
	v_cvt_pk_bf16_f32 v48, v48, v49
	v_pk_add_f32 v[130:131], v[54:55], v[130:131]
	v_cvt_pk_bf16_f32 v49, v50, v51
	v_pk_add_f32 v[130:131], v[70:71], v[130:131]
	v_cvt_pk_bf16_f32 v50, v52, v53
	v_pk_add_f32 v[130:131], v[72:73], v[130:131]
	v_cvt_pk_bf16_f32 v52, v72, v73
	v_pk_add_f32 v[130:131], v[56:57], v[130:131]
	v_cvt_pk_bf16_f32 v56, v56, v57
	v_pk_add_f32 v[130:131], v[74:75], v[130:131]
	v_cvt_pk_bf16_f32 v57, v58, v59
	v_pk_add_f32 v[130:131], v[58:59], v[130:131]
	v_cvt_pk_bf16_f32 v58, v60, v61
	v_pk_add_f32 v[130:131], v[76:77], v[130:131]
	v_cvt_pk_bf16_f32 v59, v62, v63
	v_pk_add_f32 v[130:131], v[60:61], v[130:131]
	v_cvt_pk_bf16_f32 v53, v74, v75
	v_pk_add_f32 v[130:131], v[78:79], v[130:131]
	v_cvt_pk_bf16_f32 v54, v76, v77
	v_pk_add_f32 v[130:131], v[62:63], v[130:131]
	s_waitcnt lgkmcnt(0)
	v_mfma_f32_32x32x16_bf16 v[16:31], v[64:67], v[214:217], v[16:31]
	v_cvt_pk_bf16_f32 v55, v78, v79
	v_cvt_pk_bf16_f32 v51, v70, v71
	v_add_f32_e32 v130, v130, v131
	v_add_f32_e32 v129, v129, v130
	s_waitcnt lgkmcnt(0)
	v_mfma_f32_32x32x16_bf16 v[16:31], v[52:55], v[218:221], v[16:31]
	s_waitcnt lgkmcnt(0)
	v_mfma_f32_32x32x16_bf16 v[16:31], v[48:51], v[222:225], v[16:31]
	s_waitcnt lgkmcnt(0)
	v_mfma_f32_32x32x16_bf16 v[16:31], v[56:59], v[226:229], v[16:31]
	s_waitcnt lgkmcnt(0)
	v_mfma_f32_32x32x16_bf16 v[0:15], v[64:67], v[230:233], v[0:15]
	s_waitcnt lgkmcnt(0)
	v_mfma_f32_32x32x16_bf16 v[0:15], v[52:55], v[234:237], v[0:15]
	s_waitcnt lgkmcnt(0)
	v_mfma_f32_32x32x16_bf16 v[0:15], v[48:51], v[238:241], v[0:15]
	s_waitcnt lgkmcnt(0)
	v_mfma_f32_32x32x16_bf16 v[0:15], v[56:59], v[242:245], v[0:15]
